# work rebalance: all q up-projection tiles moved to the GEMM half of the grid (GDN recurrence half was the critical path of that phase); plus ff1 and in-proj 16 B epilogue stores
# speedup vs baseline: 1.0298x; 1.0027x over previous
;     __host__ __device__ bool next(int i, Unit& u) const {
;         const long L = (long)L0 + (long)i * G + c; if (c < 0 || L >= L1) return false;
;         int wgid = (int)L; { const int q = nwg / NXCD, r = nwg % NXCD, xcd = wgid % NXCD, off = wgid / NXCD; wgid = (xcd < r ? xcd * (q + 1) : r * (q + 1) + (xcd - r) * q) + off; }
; __global__ void __launch_bounds__(512, 2) mk_fwd(Args args) {
;     ...
;         {
;             constexpr int QSPLIT = 520;
;             pg8::Gemm g = pg8::mk_gemm(WSP(bf16_t, WS_CQN), WSP(bf16_t, WS_WUQ), TR, 1536, 512, 512); pg8::StaticOrder S;
;             if (grpA) { S.init(TR, 1536, GA, bx); S.range(QSPLIT, 1 << 30); } else { S.init(TR, 1536, GBn, bx - GA); S.range(0, QSPLIT); }
;             pg8::EpiBf16<0> E{Qb, 1536};
;             pg8::gemm_phase<pg8::EpiBf16<0>, pg8::StaticOrder, true, true>(lds, g, S, E);
;         }
.LBB0_680:
	s_mov_b32 s2, 0
	s_mov_b64 s[0:1], 0x306
.LBB0_681:
	s_sub_i32 s2, s30, s2
	v_readfirstlane_b32 s12, v203
	s_cmp_lt_i32 s2, 0
	s_mov_b32 s3, 0
	s_cbranch_scc1 .LBB0_706
	s_ashr_i32 s4, s2, 31
	s_add_u32 s0, s0, s2
	s_addc_u32 s1, s1, s4
	s_movk_i32 s2, 0x306
	s_and_b64 s[4:5], s[8:9], exec
	s_cselect_b32 s2, s2, 0x306
	v_mov_b64_e32 v[0:1], s[2:3]
	v_cmp_ge_i64_e32 vcc, s[0:1], v[0:1]
	s_cbranch_vccnz .LBB0_706
	s_and_b32 s9, s0, 7
	s_cmp_gt_u32 s9, 5
	s_cbranch_scc0 .LBB0_685
	s_mul_i32 s4, s9, 0x60
	s_or_b32 s8, s4, 6
	s_cbranch_execz .LBB0_686
	s_branch .LBB0_687
